# GEMM1 plain epilogue: tiles with no q-scale (tile column >= 6) take a copy of the epilogue without the multiply-by-1.0 pass
# baseline (speedup 1.0000x reference)
; __device__ __forceinline__ unsigned cvt_pk_bf16(float lo, float hi) { const f32x2c_t v = {lo, hi}; const bf16x2c_t b = __builtin_convertvector(v, bf16x2c_t); return __builtin_bit_cast(unsigned, b); }
;     __device__ __forceinline__ void operator()(const f32x4 (&acc)[2][2][4][2], const Unit& u, int wr, int wc, int fr, int fq) const {
;     ...
;         const bool qs = u.pn < 6;
; #pragma unroll
;         for (int ai = 0; ai < 2; ++ai)
; #pragma unroll
;             for (int m = 0; m < 4; ++m) { bf16_t* rowp = Z + (size_t)(row0 + ai * HALF + m * 16) * DIN + col0;
; #pragma unroll
;                 for (int bj = 0; bj < 2; ++bj) { f32x4 v0 = acc[ai][bj][m][0], v1 = acc[ai][bj][m][1];
;                     if (qs) { v0 = v0 * QSCALE; v1 = v1 * QSCALE; }
;                     u32x4 w; w.x = cvt_pk_bf16(v0[0], v0[1]); w.y = cvt_pk_bf16(v0[2], v0[3]); w.z = cvt_pk_bf16(v1[0], v1[1]); w.w = cvt_pk_bf16(v1[2], v1[3]);
;                     *(u32x4*)(rowp + bj * HALF) = w; } }
.LBB0_287:
	v_lshl_or_b32 v158, s57, 8, v161
	v_lshl_add_u32 v163, s58, 8, v1
	v_ashrrev_i32_e32 v159, 31, v158
	v_mov_b64_e32 v[156:157], s[92:93]
	s_cmp_lt_i32 s57, 6
	s_cselect_b32 vcc_lo, s48, 1.0
	s_cbranch_scc0 .Lepz_nomul
	v_mad_i64_i32 v[164:165], s[18:19], v163, s27, v[156:157]
	v_lshlrev_b64 v[158:159], 1, v[158:159]
	v_lshl_add_u64 v[168:169], v[164:165], 0, v[158:159]
	v_pk_mul_f32 v[128:129], v[128:129], vcc op_sel_hi:[1,0]
	v_pk_mul_f32 v[126:127], v[126:127], vcc op_sel_hi:[1,0]
	v_pk_mul_f32 v[124:125], v[124:125], vcc op_sel_hi:[1,0]
	v_pk_mul_f32 v[122:123], v[122:123], vcc op_sel_hi:[1,0]
	v_cvt_pk_bf16_f32 v164, v126, v127
	v_cvt_pk_bf16_f32 v165, v128, v129
	v_cvt_pk_bf16_f32 v166, v122, v123
	v_cvt_pk_bf16_f32 v167, v124, v125
	global_store_dwordx4 v[168:169], v[164:167], off
	v_pk_mul_f32 v[116:117], v[116:117], vcc op_sel_hi:[1,0]
	v_pk_mul_f32 v[114:115], v[114:115], vcc op_sel_hi:[1,0]
	v_pk_mul_f32 v[120:121], v[120:121], vcc op_sel_hi:[1,0]
	v_pk_mul_f32 v[118:119], v[118:119], vcc op_sel_hi:[1,0]
	v_cvt_pk_bf16_f32 v164, v118, v119
	v_cvt_pk_bf16_f32 v165, v120, v121
	v_cvt_pk_bf16_f32 v166, v114, v115
	v_cvt_pk_bf16_f32 v167, v116, v117
	global_store_dwordx4 v[168:169], v[164:167], off offset:256
	v_pk_mul_f32 v[108:109], v[108:109], vcc op_sel_hi:[1,0]
	v_pk_mul_f32 v[106:107], v[106:107], vcc op_sel_hi:[1,0]
	v_or_b32_e32 v164, 16, v163
	v_mad_i64_i32 v[164:165], s[18:19], v164, s27, v[156:157]
	v_lshl_add_u64 v[168:169], v[164:165], 0, v[158:159]
	v_pk_mul_f32 v[112:113], v[112:113], vcc op_sel_hi:[1,0]
	v_pk_mul_f32 v[110:111], v[110:111], vcc op_sel_hi:[1,0]
	v_cvt_pk_bf16_f32 v164, v110, v111
	v_cvt_pk_bf16_f32 v165, v112, v113
	v_cvt_pk_bf16_f32 v166, v106, v107
	v_cvt_pk_bf16_f32 v167, v108, v109
	global_store_dwordx4 v[168:169], v[164:167], off
	v_pk_mul_f32 v[100:101], v[100:101], vcc op_sel_hi:[1,0]
	v_pk_mul_f32 v[98:99], v[98:99], vcc op_sel_hi:[1,0]
	v_pk_mul_f32 v[104:105], v[104:105], vcc op_sel_hi:[1,0]
	v_pk_mul_f32 v[102:103], v[102:103], vcc op_sel_hi:[1,0]
	v_cvt_pk_bf16_f32 v164, v102, v103
	v_cvt_pk_bf16_f32 v165, v104, v105
	v_cvt_pk_bf16_f32 v166, v98, v99
	v_cvt_pk_bf16_f32 v167, v100, v101
	global_store_dwordx4 v[168:169], v[164:167], off offset:256
	v_pk_mul_f32 v[92:93], v[92:93], vcc op_sel_hi:[1,0]
	v_pk_mul_f32 v[90:91], v[90:91], vcc op_sel_hi:[1,0]
	v_or_b32_e32 v164, 32, v163
	v_mad_i64_i32 v[164:165], s[18:19], v164, s27, v[156:157]
	v_lshl_add_u64 v[168:169], v[164:165], 0, v[158:159]
	v_pk_mul_f32 v[96:97], v[96:97], vcc op_sel_hi:[1,0]
	v_pk_mul_f32 v[94:95], v[94:95], vcc op_sel_hi:[1,0]
	v_cvt_pk_bf16_f32 v164, v94, v95
	v_cvt_pk_bf16_f32 v165, v96, v97
	v_cvt_pk_bf16_f32 v166, v90, v91
	v_cvt_pk_bf16_f32 v167, v92, v93
	global_store_dwordx4 v[168:169], v[164:167], off
	v_pk_mul_f32 v[84:85], v[84:85], vcc op_sel_hi:[1,0]
	v_pk_mul_f32 v[82:83], v[82:83], vcc op_sel_hi:[1,0]
	v_pk_mul_f32 v[88:89], v[88:89], vcc op_sel_hi:[1,0]
	v_pk_mul_f32 v[86:87], v[86:87], vcc op_sel_hi:[1,0]
	v_cvt_pk_bf16_f32 v164, v86, v87
	v_cvt_pk_bf16_f32 v165, v88, v89
	v_cvt_pk_bf16_f32 v166, v82, v83
	v_cvt_pk_bf16_f32 v167, v84, v85
	global_store_dwordx4 v[168:169], v[164:167], off offset:256
	v_pk_mul_f32 v[76:77], v[76:77], vcc op_sel_hi:[1,0]
	v_pk_mul_f32 v[74:75], v[74:75], vcc op_sel_hi:[1,0]
	v_or_b32_e32 v164, 48, v163
	v_mad_i64_i32 v[164:165], s[18:19], v164, s27, v[156:157]
	v_lshl_add_u64 v[168:169], v[164:165], 0, v[158:159]
	v_pk_mul_f32 v[80:81], v[80:81], vcc op_sel_hi:[1,0]
	v_pk_mul_f32 v[78:79], v[78:79], vcc op_sel_hi:[1,0]
	v_cvt_pk_bf16_f32 v164, v78, v79
	v_cvt_pk_bf16_f32 v165, v80, v81
	v_cvt_pk_bf16_f32 v166, v74, v75
	v_cvt_pk_bf16_f32 v167, v76, v77
	global_store_dwordx4 v[168:169], v[164:167], off
	v_pk_mul_f32 v[68:69], v[68:69], vcc op_sel_hi:[1,0]
	v_pk_mul_f32 v[66:67], v[66:67], vcc op_sel_hi:[1,0]
	v_pk_mul_f32 v[72:73], v[72:73], vcc op_sel_hi:[1,0]
	v_pk_mul_f32 v[70:71], v[70:71], vcc op_sel_hi:[1,0]
	v_cvt_pk_bf16_f32 v164, v70, v71
	v_cvt_pk_bf16_f32 v165, v72, v73
	v_cvt_pk_bf16_f32 v166, v66, v67
	v_cvt_pk_bf16_f32 v167, v68, v69
	global_store_dwordx4 v[168:169], v[164:167], off offset:256
	v_pk_mul_f32 v[60:61], v[60:61], vcc op_sel_hi:[1,0]
	v_pk_mul_f32 v[58:59], v[58:59], vcc op_sel_hi:[1,0]
	v_add_u32_e32 v164, 0x80, v163
	v_mad_i64_i32 v[164:165], s[18:19], v164, s27, v[156:157]
	v_lshl_add_u64 v[168:169], v[164:165], 0, v[158:159]
	v_pk_mul_f32 v[64:65], v[64:65], vcc op_sel_hi:[1,0]
	v_pk_mul_f32 v[62:63], v[62:63], vcc op_sel_hi:[1,0]
	v_cvt_pk_bf16_f32 v164, v62, v63
	v_cvt_pk_bf16_f32 v165, v64, v65
	v_cvt_pk_bf16_f32 v166, v58, v59
	v_cvt_pk_bf16_f32 v167, v60, v61
	global_store_dwordx4 v[168:169], v[164:167], off
	v_pk_mul_f32 v[52:53], v[52:53], vcc op_sel_hi:[1,0]
	v_pk_mul_f32 v[50:51], v[50:51], vcc op_sel_hi:[1,0]
	v_pk_mul_f32 v[56:57], v[56:57], vcc op_sel_hi:[1,0]
	v_pk_mul_f32 v[54:55], v[54:55], vcc op_sel_hi:[1,0]
	v_cvt_pk_bf16_f32 v164, v54, v55
	v_cvt_pk_bf16_f32 v165, v56, v57
	v_cvt_pk_bf16_f32 v166, v50, v51
	v_cvt_pk_bf16_f32 v167, v52, v53
	global_store_dwordx4 v[168:169], v[164:167], off offset:256
	v_pk_mul_f32 v[44:45], v[44:45], vcc op_sel_hi:[1,0]
	v_pk_mul_f32 v[42:43], v[42:43], vcc op_sel_hi:[1,0]
	v_add_u32_e32 v164, 0x90, v163
	v_mad_i64_i32 v[164:165], s[18:19], v164, s27, v[156:157]
	v_lshl_add_u64 v[168:169], v[164:165], 0, v[158:159]
	v_pk_mul_f32 v[48:49], v[48:49], vcc op_sel_hi:[1,0]
	v_pk_mul_f32 v[46:47], v[46:47], vcc op_sel_hi:[1,0]
	v_cvt_pk_bf16_f32 v164, v46, v47
	v_cvt_pk_bf16_f32 v165, v48, v49
	v_cvt_pk_bf16_f32 v166, v42, v43
	v_cvt_pk_bf16_f32 v167, v44, v45
; __device__ __forceinline__ unsigned cvt_pk_bf16(float lo, float hi) { const f32x2c_t v = {lo, hi}; const bf16x2c_t b = __builtin_convertvector(v, bf16x2c_t); return __builtin_bit_cast(unsigned, b); }
;     __device__ __forceinline__ void operator()(const f32x4 (&acc)[2][2][4][2], const Unit& u, int wr, int wc, int fr, int fq) const {
;     ...
;         const bool qs = u.pn < 6;
; #pragma unroll
;         for (int ai = 0; ai < 2; ++ai)
; #pragma unroll
;             for (int m = 0; m < 4; ++m) { bf16_t* rowp = Z + (size_t)(row0 + ai * HALF + m * 16) * DIN + col0;
; #pragma unroll
;                 for (int bj = 0; bj < 2; ++bj) { f32x4 v0 = acc[ai][bj][m][0], v1 = acc[ai][bj][m][1];
;                     if (qs) { v0 = v0 * QSCALE; v1 = v1 * QSCALE; }
;                     u32x4 w; w.x = cvt_pk_bf16(v0[0], v0[1]); w.y = cvt_pk_bf16(v0[2], v0[3]); w.z = cvt_pk_bf16(v1[0], v1[1]); w.w = cvt_pk_bf16(v1[2], v1[3]);
;                     *(u32x4*)(rowp + bj * HALF) = w; } }
	global_store_dwordx4 v[168:169], v[164:167], off
	v_pk_mul_f32 v[36:37], v[36:37], vcc op_sel_hi:[1,0]
	v_pk_mul_f32 v[34:35], v[34:35], vcc op_sel_hi:[1,0]
	v_pk_mul_f32 v[40:41], v[40:41], vcc op_sel_hi:[1,0]
	v_pk_mul_f32 v[38:39], v[38:39], vcc op_sel_hi:[1,0]
	v_cvt_pk_bf16_f32 v164, v38, v39
	v_cvt_pk_bf16_f32 v165, v40, v41
	v_cvt_pk_bf16_f32 v166, v34, v35
	v_cvt_pk_bf16_f32 v167, v36, v37
	global_store_dwordx4 v[168:169], v[164:167], off offset:256
	v_pk_mul_f32 v[28:29], v[28:29], vcc op_sel_hi:[1,0]
	v_pk_mul_f32 v[26:27], v[26:27], vcc op_sel_hi:[1,0]
	v_add_u32_e32 v164, 0xa0, v163
	v_mad_i64_i32 v[164:165], s[18:19], v164, s27, v[156:157]
	v_lshl_add_u64 v[168:169], v[164:165], 0, v[158:159]
	v_pk_mul_f32 v[32:33], v[32:33], vcc op_sel_hi:[1,0]
	v_pk_mul_f32 v[30:31], v[30:31], vcc op_sel_hi:[1,0]
	v_cvt_pk_bf16_f32 v164, v30, v31
	v_cvt_pk_bf16_f32 v165, v32, v33
	v_cvt_pk_bf16_f32 v166, v26, v27
	v_cvt_pk_bf16_f32 v167, v28, v29
	global_store_dwordx4 v[168:169], v[164:167], off
	v_pk_mul_f32 v[20:21], v[20:21], vcc op_sel_hi:[1,0]
	v_pk_mul_f32 v[18:19], v[18:19], vcc op_sel_hi:[1,0]
	v_pk_mul_f32 v[24:25], v[24:25], vcc op_sel_hi:[1,0]
	v_pk_mul_f32 v[22:23], v[22:23], vcc op_sel_hi:[1,0]
	v_add_u32_e32 v163, 0xb0, v163
	v_cvt_pk_bf16_f32 v164, v22, v23
	v_cvt_pk_bf16_f32 v165, v24, v25
	v_cvt_pk_bf16_f32 v166, v18, v19
	v_cvt_pk_bf16_f32 v167, v20, v21
	v_mad_i64_i32 v[156:157], s[18:19], v163, s27, v[156:157]
	global_store_dwordx4 v[168:169], v[164:167], off offset:256
	v_pk_mul_f32 v[10:11], v[10:11], vcc op_sel_hi:[1,0]
	s_nop 0
	v_lshl_add_u64 v[164:165], v[156:157], 0, v[158:159]
	v_pk_mul_f32 v[16:17], v[16:17], vcc op_sel_hi:[1,0]
	v_pk_mul_f32 v[14:15], v[14:15], vcc op_sel_hi:[1,0]
	v_pk_mul_f32 v[12:13], v[12:13], vcc op_sel_hi:[1,0]
	v_cvt_pk_bf16_f32 v156, v14, v15
	v_cvt_pk_bf16_f32 v157, v16, v17
	v_cvt_pk_bf16_f32 v158, v10, v11
	v_cvt_pk_bf16_f32 v159, v12, v13
	global_store_dwordx4 v[164:165], v[156:159], off
	v_pk_mul_f32 v[4:5], v[4:5], vcc op_sel_hi:[1,0]
	v_pk_mul_f32 v[2:3], v[2:3], vcc op_sel_hi:[1,0]
	v_pk_mul_f32 v[8:9], v[8:9], vcc op_sel_hi:[1,0]
	v_pk_mul_f32 v[6:7], v[6:7], vcc op_sel_hi:[1,0]
	v_cvt_pk_bf16_f32 v156, v6, v7
	v_cvt_pk_bf16_f32 v157, v8, v9
	v_cvt_pk_bf16_f32 v158, v2, v3
	v_cvt_pk_bf16_f32 v159, v4, v5
	global_store_dwordx4 v[164:165], v[156:159], off offset:256
	s_cbranch_execnz .LBB0_285
	s_branch .LBB0_288
.Lepz_nomul:
	v_mad_i64_i32 v[164:165], s[18:19], v163, s27, v[156:157]
	v_lshlrev_b64 v[158:159], 1, v[158:159]
	v_lshl_add_u64 v[168:169], v[164:165], 0, v[158:159]
	v_cvt_pk_bf16_f32 v164, v126, v127
	v_cvt_pk_bf16_f32 v165, v128, v129
	v_cvt_pk_bf16_f32 v166, v122, v123
	v_cvt_pk_bf16_f32 v167, v124, v125
	global_store_dwordx4 v[168:169], v[164:167], off
	s_nop 1
	v_cvt_pk_bf16_f32 v164, v118, v119
	v_cvt_pk_bf16_f32 v165, v120, v121
	v_cvt_pk_bf16_f32 v166, v114, v115
	v_cvt_pk_bf16_f32 v167, v116, v117
	global_store_dwordx4 v[168:169], v[164:167], off offset:256
	s_nop 1
	v_or_b32_e32 v164, 16, v163
	v_mad_i64_i32 v[164:165], s[18:19], v164, s27, v[156:157]
	v_lshl_add_u64 v[168:169], v[164:165], 0, v[158:159]
	v_cvt_pk_bf16_f32 v164, v110, v111
	v_cvt_pk_bf16_f32 v165, v112, v113
	v_cvt_pk_bf16_f32 v166, v106, v107
	v_cvt_pk_bf16_f32 v167, v108, v109
	global_store_dwordx4 v[168:169], v[164:167], off
	s_nop 1
	v_cvt_pk_bf16_f32 v164, v102, v103
	v_cvt_pk_bf16_f32 v165, v104, v105
	v_cvt_pk_bf16_f32 v166, v98, v99
	v_cvt_pk_bf16_f32 v167, v100, v101
	global_store_dwordx4 v[168:169], v[164:167], off offset:256
	s_nop 1
	v_or_b32_e32 v164, 32, v163
	v_mad_i64_i32 v[164:165], s[18:19], v164, s27, v[156:157]
	v_lshl_add_u64 v[168:169], v[164:165], 0, v[158:159]
	v_cvt_pk_bf16_f32 v164, v94, v95
	v_cvt_pk_bf16_f32 v165, v96, v97
	v_cvt_pk_bf16_f32 v166, v90, v91
	v_cvt_pk_bf16_f32 v167, v92, v93
	global_store_dwordx4 v[168:169], v[164:167], off
	s_nop 1
	v_cvt_pk_bf16_f32 v164, v86, v87
	v_cvt_pk_bf16_f32 v165, v88, v89
	v_cvt_pk_bf16_f32 v166, v82, v83
	v_cvt_pk_bf16_f32 v167, v84, v85
	global_store_dwordx4 v[168:169], v[164:167], off offset:256
	s_nop 1
	v_or_b32_e32 v164, 48, v163
	v_mad_i64_i32 v[164:165], s[18:19], v164, s27, v[156:157]
	v_lshl_add_u64 v[168:169], v[164:165], 0, v[158:159]
	v_cvt_pk_bf16_f32 v164, v78, v79
	v_cvt_pk_bf16_f32 v165, v80, v81
	v_cvt_pk_bf16_f32 v166, v74, v75
	v_cvt_pk_bf16_f32 v167, v76, v77
	global_store_dwordx4 v[168:169], v[164:167], off
	s_nop 1
	v_cvt_pk_bf16_f32 v164, v70, v71
	v_cvt_pk_bf16_f32 v165, v72, v73
	v_cvt_pk_bf16_f32 v166, v66, v67
	v_cvt_pk_bf16_f32 v167, v68, v69
	global_store_dwordx4 v[168:169], v[164:167], off offset:256
	s_nop 1
	v_add_u32_e32 v164, 0x80, v163
	v_mad_i64_i32 v[164:165], s[18:19], v164, s27, v[156:157]
	v_lshl_add_u64 v[168:169], v[164:165], 0, v[158:159]
	v_cvt_pk_bf16_f32 v164, v62, v63
	v_cvt_pk_bf16_f32 v165, v64, v65
	v_cvt_pk_bf16_f32 v166, v58, v59
	v_cvt_pk_bf16_f32 v167, v60, v61
	global_store_dwordx4 v[168:169], v[164:167], off
	s_nop 1
	v_cvt_pk_bf16_f32 v164, v54, v55
	v_cvt_pk_bf16_f32 v165, v56, v57
	v_cvt_pk_bf16_f32 v166, v50, v51
	v_cvt_pk_bf16_f32 v167, v52, v53
	global_store_dwordx4 v[168:169], v[164:167], off offset:256
	s_nop 1
	v_add_u32_e32 v164, 0x90, v163
	v_mad_i64_i32 v[164:165], s[18:19], v164, s27, v[156:157]
	v_lshl_add_u64 v[168:169], v[164:165], 0, v[158:159]
	v_cvt_pk_bf16_f32 v164, v46, v47
	v_cvt_pk_bf16_f32 v165, v48, v49
	v_cvt_pk_bf16_f32 v166, v42, v43
	v_cvt_pk_bf16_f32 v167, v44, v45
	global_store_dwordx4 v[168:169], v[164:167], off
	s_nop 1
	v_cvt_pk_bf16_f32 v164, v38, v39
	v_cvt_pk_bf16_f32 v165, v40, v41
	v_cvt_pk_bf16_f32 v166, v34, v35
	v_cvt_pk_bf16_f32 v167, v36, v37
	global_store_dwordx4 v[168:169], v[164:167], off offset:256
	s_nop 1
	v_add_u32_e32 v164, 0xa0, v163
	v_mad_i64_i32 v[164:165], s[18:19], v164, s27, v[156:157]
	v_lshl_add_u64 v[168:169], v[164:165], 0, v[158:159]
	v_cvt_pk_bf16_f32 v164, v30, v31
	v_cvt_pk_bf16_f32 v165, v32, v33
	v_cvt_pk_bf16_f32 v166, v26, v27
	v_cvt_pk_bf16_f32 v167, v28, v29
	global_store_dwordx4 v[168:169], v[164:167], off
	s_nop 1
	v_add_u32_e32 v163, 0xb0, v163
	v_cvt_pk_bf16_f32 v164, v22, v23
	v_cvt_pk_bf16_f32 v165, v24, v25
	v_cvt_pk_bf16_f32 v166, v18, v19
	v_cvt_pk_bf16_f32 v167, v20, v21
	v_mad_i64_i32 v[156:157], s[18:19], v163, s27, v[156:157]
	global_store_dwordx4 v[168:169], v[164:167], off offset:256
	s_nop 1
	s_nop 0
	v_lshl_add_u64 v[164:165], v[156:157], 0, v[158:159]
	v_cvt_pk_bf16_f32 v156, v14, v15
	v_cvt_pk_bf16_f32 v157, v16, v17
	v_cvt_pk_bf16_f32 v158, v10, v11
	v_cvt_pk_bf16_f32 v159, v12, v13
	global_store_dwordx4 v[164:165], v[156:159], off
	s_nop 1
	v_cvt_pk_bf16_f32 v156, v6, v7
	v_cvt_pk_bf16_f32 v157, v8, v9
	v_cvt_pk_bf16_f32 v158, v2, v3
	v_cvt_pk_bf16_f32 v159, v4, v5
	global_store_dwordx4 v[164:165], v[156:159], off offset:256
	s_nop 1
	s_branch .LBB0_285
